# GEMM epilogue stores issued at agent scope (sc1, written through L2) so the grid barrier's release fence has less dirty data to flush; on top of v76
# speedup vs baseline: 1.0535x; 1.0084x over previous
.Lpfa_skip_ip:
	s_mov_b32 s99, 1
	v_or_b32_e32 v1, s25, v238
	v_and_b32_e32 v0, 0xc0, v203
	v_add_u32_e32 v8, v1, v239
	v_lshlrev_b32_e32 v1, 2, v201
	v_or3_b32 v6, v1, v0, s34
	v_mov_b64_e32 v[0:1], s[30:31]
	v_mad_i64_i32 v[2:3], s[10:11], v8, s33, v[0:1]
	v_lshlrev_b32_e32 v6, 1, v6
	v_and_b32_e32 v9, 1, v201
	v_mul_u32_u24_e32 v9, 24, v9
	v_add_u32_e32 v6, v6, v9
	v_mov_b32_e32 v7, v17
	v_cvt_pk_bf16_f32 v10, v158, v159
	v_cvt_pk_bf16_f32 v11, v160, v161
	v_cvt_pk_bf16_f32 v12, v154, v155
	v_cvt_pk_bf16_f32 v13, v156, v157
	v_cvt_pk_bf16_f32 v162, v150, v151
	v_cvt_pk_bf16_f32 v163, v152, v153
	v_cvt_pk_bf16_f32 v164, v146, v147
	v_cvt_pk_bf16_f32 v165, v148, v149
	v_lshl_add_u64 v[2:3], v[2:3], 0, v[6:7]
	s_nop 1
	v_permlane16_swap_b32 v10, v12
	v_permlane16_swap_b32 v11, v13
	v_permlane16_swap_b32 v162, v164
	v_permlane16_swap_b32 v163, v165
	s_nop 1
	global_store_dwordx4 v[2:3], v[10:13], off sc1
	global_store_dwordx4 v[2:3], v[162:165], off offset:64 sc1
	v_cvt_pk_bf16_f32 v166, v142, v143
	v_cvt_pk_bf16_f32 v167, v144, v145
	v_cvt_pk_bf16_f32 v168, v138, v139
	v_cvt_pk_bf16_f32 v169, v140, v141
	v_cvt_pk_bf16_f32 v170, v134, v135
	v_cvt_pk_bf16_f32 v171, v136, v137
	v_cvt_pk_bf16_f32 v172, v130, v131
	v_cvt_pk_bf16_f32 v173, v132, v133
	v_or_b32_e32 v2, 16, v8
	v_mad_i64_i32 v[2:3], s[10:11], v2, s33, v[0:1]
	v_lshl_add_u64 v[2:3], v[2:3], 0, v[6:7]
	s_nop 1
	v_permlane16_swap_b32 v166, v168
	v_permlane16_swap_b32 v167, v169
	v_permlane16_swap_b32 v170, v172
	v_permlane16_swap_b32 v171, v173
	s_nop 1
	global_store_dwordx4 v[2:3], v[166:169], off sc1
	global_store_dwordx4 v[2:3], v[170:173], off offset:64 sc1
	v_cvt_pk_bf16_f32 v10, v126, v127
	v_cvt_pk_bf16_f32 v11, v128, v129
	v_cvt_pk_bf16_f32 v12, v122, v123
	v_cvt_pk_bf16_f32 v13, v124, v125
	v_cvt_pk_bf16_f32 v162, v118, v119
	v_cvt_pk_bf16_f32 v163, v120, v121
	v_cvt_pk_bf16_f32 v164, v114, v115
	v_cvt_pk_bf16_f32 v165, v116, v117
	v_or_b32_e32 v2, 32, v8
	v_mad_i64_i32 v[2:3], s[10:11], v2, s33, v[0:1]
	v_lshl_add_u64 v[2:3], v[2:3], 0, v[6:7]
	s_nop 1
	v_permlane16_swap_b32 v10, v12
	v_permlane16_swap_b32 v11, v13
	v_permlane16_swap_b32 v162, v164
	v_permlane16_swap_b32 v163, v165
	s_nop 1
	global_store_dwordx4 v[2:3], v[10:13], off sc1
	global_store_dwordx4 v[2:3], v[162:165], off offset:64 sc1
	v_cvt_pk_bf16_f32 v166, v110, v111
	v_cvt_pk_bf16_f32 v167, v112, v113
	v_cvt_pk_bf16_f32 v168, v106, v107
	v_cvt_pk_bf16_f32 v169, v108, v109
	v_cvt_pk_bf16_f32 v170, v102, v103
	v_cvt_pk_bf16_f32 v171, v104, v105
	v_cvt_pk_bf16_f32 v172, v86, v87
	v_cvt_pk_bf16_f32 v173, v88, v89
	v_or_b32_e32 v2, 48, v8
	v_mad_i64_i32 v[2:3], s[10:11], v2, s33, v[0:1]
	v_lshl_add_u64 v[2:3], v[2:3], 0, v[6:7]
	s_nop 1
	v_permlane16_swap_b32 v166, v168
	v_permlane16_swap_b32 v167, v169
	v_permlane16_swap_b32 v170, v172
	v_permlane16_swap_b32 v171, v173
	s_nop 1
	global_store_dwordx4 v[2:3], v[166:169], off sc1
	global_store_dwordx4 v[2:3], v[170:173], off offset:64 sc1
	v_cvt_pk_bf16_f32 v10, v94, v95
	v_cvt_pk_bf16_f32 v11, v96, v97
	v_cvt_pk_bf16_f32 v12, v82, v83
	v_cvt_pk_bf16_f32 v13, v84, v85
	v_cvt_pk_bf16_f32 v162, v78, v79
	v_cvt_pk_bf16_f32 v163, v80, v81
	v_cvt_pk_bf16_f32 v164, v70, v71
	v_cvt_pk_bf16_f32 v165, v72, v73
	v_or_b32_e32 v2, 64, v8
	v_mad_i64_i32 v[2:3], s[10:11], v2, s33, v[0:1]
	v_lshl_add_u64 v[2:3], v[2:3], 0, v[6:7]
	s_nop 1
	v_permlane16_swap_b32 v10, v12
	v_permlane16_swap_b32 v11, v13
	v_permlane16_swap_b32 v162, v164
	v_permlane16_swap_b32 v163, v165
	s_nop 1
	global_store_dwordx4 v[2:3], v[10:13], off sc1
	global_store_dwordx4 v[2:3], v[162:165], off offset:64 sc1
	v_cvt_pk_bf16_f32 v166, v66, v67
	v_cvt_pk_bf16_f32 v167, v68, v69
	v_cvt_pk_bf16_f32 v168, v62, v63
	v_cvt_pk_bf16_f32 v169, v64, v65
	v_cvt_pk_bf16_f32 v170, v46, v47
	v_cvt_pk_bf16_f32 v171, v48, v49
	v_cvt_pk_bf16_f32 v172, v42, v43
	v_cvt_pk_bf16_f32 v173, v44, v45
	v_or_b32_e32 v2, 0x50, v8
	v_mad_i64_i32 v[2:3], s[10:11], v2, s33, v[0:1]
	v_lshl_add_u64 v[2:3], v[2:3], 0, v[6:7]
	s_nop 1
	v_permlane16_swap_b32 v166, v168
	v_permlane16_swap_b32 v167, v169
	v_permlane16_swap_b32 v170, v172
	v_permlane16_swap_b32 v171, v173
	s_nop 1
	global_store_dwordx4 v[2:3], v[166:169], off sc1
	global_store_dwordx4 v[2:3], v[170:173], off offset:64 sc1
	v_cvt_pk_bf16_f32 v10, v34, v35
	v_cvt_pk_bf16_f32 v11, v36, v37
	v_cvt_pk_bf16_f32 v12, v30, v31
	v_cvt_pk_bf16_f32 v13, v32, v33
	v_cvt_pk_bf16_f32 v162, v26, v27
	v_cvt_pk_bf16_f32 v163, v28, v29
	v_cvt_pk_bf16_f32 v164, v22, v23
	v_cvt_pk_bf16_f32 v165, v24, v25
	v_or_b32_e32 v2, 0x60, v8
	v_mad_i64_i32 v[2:3], s[10:11], v2, s33, v[0:1]
	v_lshl_add_u64 v[2:3], v[2:3], 0, v[6:7]
	s_nop 1
	v_permlane16_swap_b32 v10, v12
	v_permlane16_swap_b32 v11, v13
	v_permlane16_swap_b32 v162, v164
	v_permlane16_swap_b32 v163, v165
	s_nop 1
	global_store_dwordx4 v[2:3], v[10:13], off sc1
	global_store_dwordx4 v[2:3], v[162:165], off offset:64 sc1
	v_cvt_pk_bf16_f32 v166, v18, v19
	v_cvt_pk_bf16_f32 v167, v20, v21
	v_cvt_pk_bf16_f32 v168, v98, v99
	v_cvt_pk_bf16_f32 v169, v100, v101
	v_cvt_pk_bf16_f32 v170, v90, v91
	v_cvt_pk_bf16_f32 v171, v92, v93
	v_cvt_pk_bf16_f32 v172, v74, v75
	v_cvt_pk_bf16_f32 v173, v76, v77
	v_or_b32_e32 v2, 0x70, v8
	v_mad_i64_i32 v[0:1], s[10:11], v2, s33, v[0:1]
	v_lshl_add_u64 v[0:1], v[0:1], 0, v[6:7]
	s_mov_b64 s[10:11], 0
	s_nop 1
	v_permlane16_swap_b32 v166, v168
	v_permlane16_swap_b32 v167, v169
	v_permlane16_swap_b32 v170, v172
	v_permlane16_swap_b32 v171, v173
	s_nop 1
	global_store_dwordx4 v[0:1], v[166:169], off sc1
	global_store_dwordx4 v[0:1], v[170:173], off offset:64 sc1

.LBB0_955:
	v_or_b32_e32 v0, s34, v129
	v_and_b32_e32 v1, 64, v128
	v_add_u32_e32 v0, v0, v130
	v_lshlrev_b32_e32 v2, 2, v127
	v_or3_b32 v6, v2, v1, s25
	v_ashrrev_i32_e32 v1, 31, v0
	v_lshlrev_b64 v[2:3], 11, v[0:1]
	v_lshl_add_u64 v[2:3], s[6:7], 0, v[2:3]
	v_lshlrev_b32_e32 v6, 1, v6
	v_and_b32_e32 v9, 1, v127
	v_mul_u32_u24_e32 v9, 24, v9
	v_add_u32_e32 v6, v6, v9
	v_mov_b32_e32 v7, v17
	v_cvt_pk_bf16_f32 v160, v46, v47
	v_cvt_pk_bf16_f32 v161, v48, v49
	v_cvt_pk_bf16_f32 v162, v42, v43
	v_cvt_pk_bf16_f32 v163, v44, v45
	v_cvt_pk_bf16_f32 v164, v34, v35
	v_cvt_pk_bf16_f32 v165, v36, v37
	v_cvt_pk_bf16_f32 v166, v22, v23
	v_cvt_pk_bf16_f32 v167, v24, v25
	v_lshl_add_u64 v[2:3], v[2:3], 0, v[6:7]
	s_nop 1
	v_permlane16_swap_b32 v160, v162
	v_permlane16_swap_b32 v161, v163
	v_permlane16_swap_b32 v164, v166
	v_permlane16_swap_b32 v165, v167
	s_nop 1
	global_store_dwordx4 v[2:3], v[160:163], off sc1
	global_store_dwordx4 v[2:3], v[164:167], off offset:64 sc1
	v_cvt_pk_bf16_f32 v168, v30, v31
	v_cvt_pk_bf16_f32 v169, v32, v33
	v_cvt_pk_bf16_f32 v170, v18, v19
	v_cvt_pk_bf16_f32 v171, v20, v21
	v_cvt_pk_bf16_f32 v172, v38, v39
	v_cvt_pk_bf16_f32 v173, v40, v41
	v_cvt_pk_bf16_f32 v174, v26, v27
	v_cvt_pk_bf16_f32 v175, v28, v29
	v_or_b32_e32 v2, 16, v0
	v_ashrrev_i32_e32 v3, 31, v2
	v_lshlrev_b64 v[2:3], 11, v[2:3]
	v_lshl_add_u64 v[2:3], s[6:7], 0, v[2:3]
	v_lshl_add_u64 v[2:3], v[2:3], 0, v[6:7]
	s_nop 1
	v_permlane16_swap_b32 v168, v170
	v_permlane16_swap_b32 v169, v171
	v_permlane16_swap_b32 v172, v174
	v_permlane16_swap_b32 v173, v175
	s_nop 1
	global_store_dwordx4 v[2:3], v[168:171], off sc1
	global_store_dwordx4 v[2:3], v[172:175], off offset:64 sc1
	v_cvt_pk_bf16_f32 v160, v70, v71
	v_cvt_pk_bf16_f32 v161, v72, v73
	v_cvt_pk_bf16_f32 v162, v66, v67
	v_cvt_pk_bf16_f32 v163, v68, v69
	v_cvt_pk_bf16_f32 v164, v62, v63
	v_cvt_pk_bf16_f32 v165, v64, v65
	v_cvt_pk_bf16_f32 v166, v58, v59
	v_cvt_pk_bf16_f32 v167, v60, v61
	v_or_b32_e32 v2, 32, v0
	v_ashrrev_i32_e32 v3, 31, v2
	v_lshlrev_b64 v[2:3], 11, v[2:3]
	v_lshl_add_u64 v[2:3], s[6:7], 0, v[2:3]
	v_lshl_add_u64 v[2:3], v[2:3], 0, v[6:7]
	v_or_b32_e32 v0, 48, v0
	v_ashrrev_i32_e32 v1, 31, v0
	v_lshlrev_b64 v[0:1], 11, v[0:1]
	v_lshl_add_u64 v[0:1], s[6:7], 0, v[0:1]
	s_nop 1
	v_permlane16_swap_b32 v160, v162
	v_permlane16_swap_b32 v161, v163
	v_permlane16_swap_b32 v164, v166
	v_permlane16_swap_b32 v165, v167
	s_nop 1
	global_store_dwordx4 v[2:3], v[160:163], off sc1
	global_store_dwordx4 v[2:3], v[164:167], off offset:64 sc1
	v_cvt_pk_bf16_f32 v168, v78, v79
	v_cvt_pk_bf16_f32 v169, v80, v81
	v_cvt_pk_bf16_f32 v170, v74, v75
	v_cvt_pk_bf16_f32 v171, v76, v77
	v_cvt_pk_bf16_f32 v172, v82, v83
	v_cvt_pk_bf16_f32 v173, v84, v85
	v_cvt_pk_bf16_f32 v174, v86, v87
	v_cvt_pk_bf16_f32 v175, v88, v89
	v_lshl_add_u64 v[0:1], v[0:1], 0, v[6:7]
	s_nop 1
	v_permlane16_swap_b32 v168, v170
	v_permlane16_swap_b32 v169, v171
	v_permlane16_swap_b32 v172, v174
	v_permlane16_swap_b32 v173, v175
	s_nop 1
	global_store_dwordx4 v[0:1], v[168:171], off sc1
	global_store_dwordx4 v[0:1], v[172:175], off offset:64 sc1

.Lpfa_skip_m1:
	s_mov_b32 s99, 1
	v_and_b32_e32 v70, 0xc0, v203
	v_or_b32_e32 v70, s43, v70
	v_lshrrev_b32_e32 v70, 5, v70
	v_mul_u32_u24_e32 v70, 0x9000, v70
	v_or_b32_e32 v71, s34, v238
	v_add3_u32 v70, v71, v239, v70
	v_lshlrev_b32_e32 v70, 6, v70
	v_lshlrev_b32_e32 v71, 3, v201
	v_and_b32_e32 v72, 1, v201
	v_mul_u32_u24_e32 v72, 24, v72
	v_add3_u32 v70, v70, v71, v72
	v_mov_b32_e32 v71, v17
	s_mov_b64 s[40:41], 0x1000
	v_lshl_add_u64 v[86:87], s[30:31], 0, v[70:71]
	v_lshl_add_u64 v[88:89], v[86:87], 0, s[40:41]
	s_mov_b64 s[40:41], 0x240000
	v_lshl_add_u64 v[118:119], v[86:87], 0, s[40:41]
	v_lshl_add_u64 v[120:121], v[88:89], 0, s[40:41]
	v_max_f32_e32 v78, 0, v158
	v_max_f32_e32 v79, 0, v159
	v_max_f32_e32 v80, 0, v160
	v_max_f32_e32 v81, 0, v161
	v_pk_mul_f32 v[78:79], v[78:79], v[78:79]
	v_pk_mul_f32 v[80:81], v[80:81], v[80:81]
	v_cvt_pk_bf16_f32 v162, v78, v79
	v_cvt_pk_bf16_f32 v163, v80, v81
	v_max_f32_e32 v82, 0, v154
	v_max_f32_e32 v83, 0, v155
	v_max_f32_e32 v84, 0, v156
	v_max_f32_e32 v85, 0, v157
	v_pk_mul_f32 v[82:83], v[82:83], v[82:83]
	v_pk_mul_f32 v[84:85], v[84:85], v[84:85]
	v_cvt_pk_bf16_f32 v164, v82, v83
	v_cvt_pk_bf16_f32 v165, v84, v85
	v_max_f32_e32 v78, 0, v150
	v_max_f32_e32 v79, 0, v151
	v_max_f32_e32 v80, 0, v152
	v_max_f32_e32 v81, 0, v153
	v_pk_mul_f32 v[78:79], v[78:79], v[78:79]
	v_pk_mul_f32 v[80:81], v[80:81], v[80:81]
	v_cvt_pk_bf16_f32 v166, v78, v79
	v_cvt_pk_bf16_f32 v167, v80, v81
	v_max_f32_e32 v82, 0, v146
	v_max_f32_e32 v83, 0, v147
	v_max_f32_e32 v84, 0, v148
	v_max_f32_e32 v85, 0, v149
	v_pk_mul_f32 v[82:83], v[82:83], v[82:83]
	v_pk_mul_f32 v[84:85], v[84:85], v[84:85]
	v_cvt_pk_bf16_f32 v168, v82, v83
	v_cvt_pk_bf16_f32 v169, v84, v85
	s_nop 1
	v_permlane16_swap_b32 v162, v164
	v_permlane16_swap_b32 v163, v165
	v_permlane16_swap_b32 v166, v168
	v_permlane16_swap_b32 v167, v169
	s_nop 1
	global_store_dwordx4 v[86:87], v[162:165], off sc1
	global_store_dwordx4 v[118:119], v[166:169], off sc1
	v_max_f32_e32 v78, 0, v142
	v_max_f32_e32 v79, 0, v143
	v_max_f32_e32 v80, 0, v144
	v_max_f32_e32 v81, 0, v145
	v_pk_mul_f32 v[78:79], v[78:79], v[78:79]
	v_pk_mul_f32 v[80:81], v[80:81], v[80:81]
	v_cvt_pk_bf16_f32 v170, v78, v79
	v_cvt_pk_bf16_f32 v171, v80, v81
	v_max_f32_e32 v82, 0, v138
	v_max_f32_e32 v83, 0, v139
	v_max_f32_e32 v84, 0, v140
	v_max_f32_e32 v85, 0, v141
	v_pk_mul_f32 v[82:83], v[82:83], v[82:83]
	v_pk_mul_f32 v[84:85], v[84:85], v[84:85]
	v_cvt_pk_bf16_f32 v172, v82, v83
	v_cvt_pk_bf16_f32 v173, v84, v85
	v_max_f32_e32 v78, 0, v134
	v_max_f32_e32 v79, 0, v135
	v_max_f32_e32 v80, 0, v136
	v_max_f32_e32 v81, 0, v137
	v_pk_mul_f32 v[78:79], v[78:79], v[78:79]
	v_pk_mul_f32 v[80:81], v[80:81], v[80:81]
	v_cvt_pk_bf16_f32 v174, v78, v79
	v_cvt_pk_bf16_f32 v175, v80, v81
	v_max_f32_e32 v82, 0, v114
	v_max_f32_e32 v83, 0, v115
	v_max_f32_e32 v84, 0, v116
	v_max_f32_e32 v85, 0, v117
	v_pk_mul_f32 v[82:83], v[82:83], v[82:83]
	v_pk_mul_f32 v[84:85], v[84:85], v[84:85]
	v_cvt_pk_bf16_f32 v176, v82, v83
	v_cvt_pk_bf16_f32 v177, v84, v85
	s_nop 1
	v_permlane16_swap_b32 v170, v172
	v_permlane16_swap_b32 v171, v173
	v_permlane16_swap_b32 v174, v176
	v_permlane16_swap_b32 v175, v177
	s_nop 1
	global_store_dwordx4 v[86:87], v[170:173], off offset:1024 sc1
	global_store_dwordx4 v[118:119], v[174:177], off offset:1024 sc1
	v_max_f32_e32 v78, 0, v110
	v_max_f32_e32 v79, 0, v111
	v_max_f32_e32 v80, 0, v112
	v_max_f32_e32 v81, 0, v113
	v_pk_mul_f32 v[78:79], v[78:79], v[78:79]
	v_pk_mul_f32 v[80:81], v[80:81], v[80:81]
	v_cvt_pk_bf16_f32 v162, v78, v79
	v_cvt_pk_bf16_f32 v163, v80, v81
	v_max_f32_e32 v82, 0, v106
	v_max_f32_e32 v83, 0, v107
	v_max_f32_e32 v84, 0, v108
	v_max_f32_e32 v85, 0, v109
	v_pk_mul_f32 v[82:83], v[82:83], v[82:83]
	v_pk_mul_f32 v[84:85], v[84:85], v[84:85]
	v_cvt_pk_bf16_f32 v164, v82, v83
	v_cvt_pk_bf16_f32 v165, v84, v85
	v_max_f32_e32 v78, 0, v102
	v_max_f32_e32 v79, 0, v103
	v_max_f32_e32 v80, 0, v104
	v_max_f32_e32 v81, 0, v105
	v_pk_mul_f32 v[78:79], v[78:79], v[78:79]
	v_pk_mul_f32 v[80:81], v[80:81], v[80:81]
	v_cvt_pk_bf16_f32 v166, v78, v79
	v_cvt_pk_bf16_f32 v167, v80, v81
	v_max_f32_e32 v82, 0, v98
	v_max_f32_e32 v83, 0, v99
	v_max_f32_e32 v84, 0, v100
	v_max_f32_e32 v85, 0, v101
	v_pk_mul_f32 v[82:83], v[82:83], v[82:83]
	v_pk_mul_f32 v[84:85], v[84:85], v[84:85]
	v_cvt_pk_bf16_f32 v168, v82, v83
	v_cvt_pk_bf16_f32 v169, v84, v85
	s_nop 1
	v_permlane16_swap_b32 v162, v164
	v_permlane16_swap_b32 v163, v165
	v_permlane16_swap_b32 v166, v168
	v_permlane16_swap_b32 v167, v169
	s_nop 1
	global_store_dwordx4 v[86:87], v[162:165], off offset:2048 sc1
	global_store_dwordx4 v[118:119], v[166:169], off offset:2048 sc1
	v_max_f32_e32 v78, 0, v94
	v_max_f32_e32 v79, 0, v95
	v_max_f32_e32 v80, 0, v96
	v_max_f32_e32 v81, 0, v97
	v_pk_mul_f32 v[78:79], v[78:79], v[78:79]
	v_pk_mul_f32 v[80:81], v[80:81], v[80:81]
	v_cvt_pk_bf16_f32 v170, v78, v79
	v_cvt_pk_bf16_f32 v171, v80, v81
	v_max_f32_e32 v82, 0, v90
	v_max_f32_e32 v83, 0, v91
	v_max_f32_e32 v84, 0, v92
	v_max_f32_e32 v85, 0, v93
	v_pk_mul_f32 v[82:83], v[82:83], v[82:83]
	v_pk_mul_f32 v[84:85], v[84:85], v[84:85]
	v_cvt_pk_bf16_f32 v172, v82, v83
	v_cvt_pk_bf16_f32 v173, v84, v85
	v_max_f32_e32 v78, 0, v74
	v_max_f32_e32 v79, 0, v75
	v_max_f32_e32 v80, 0, v76
	v_max_f32_e32 v81, 0, v77
	v_pk_mul_f32 v[78:79], v[78:79], v[78:79]
	v_pk_mul_f32 v[80:81], v[80:81], v[80:81]
	v_cvt_pk_bf16_f32 v174, v78, v79
	v_cvt_pk_bf16_f32 v175, v80, v81
	v_max_f32_e32 v82, 0, v66
	v_max_f32_e32 v83, 0, v67
	v_max_f32_e32 v84, 0, v68
	v_max_f32_e32 v85, 0, v69
	v_pk_mul_f32 v[82:83], v[82:83], v[82:83]
	v_pk_mul_f32 v[84:85], v[84:85], v[84:85]
	v_cvt_pk_bf16_f32 v176, v82, v83
	v_cvt_pk_bf16_f32 v177, v84, v85
	s_nop 1
	v_permlane16_swap_b32 v170, v172
	v_permlane16_swap_b32 v171, v173
	v_permlane16_swap_b32 v174, v176
	v_permlane16_swap_b32 v175, v177
	s_nop 1
	global_store_dwordx4 v[86:87], v[170:173], off offset:3072 sc1
	global_store_dwordx4 v[118:119], v[174:177], off offset:3072 sc1
	v_max_f32_e32 v78, 0, v62
	v_max_f32_e32 v79, 0, v63
	v_max_f32_e32 v80, 0, v64
	v_max_f32_e32 v81, 0, v65
	v_pk_mul_f32 v[78:79], v[78:79], v[78:79]
	v_pk_mul_f32 v[80:81], v[80:81], v[80:81]
	v_cvt_pk_bf16_f32 v162, v78, v79
	v_cvt_pk_bf16_f32 v163, v80, v81
	v_max_f32_e32 v82, 0, v58
	v_max_f32_e32 v83, 0, v59
	v_max_f32_e32 v84, 0, v60
	v_max_f32_e32 v85, 0, v61
	v_pk_mul_f32 v[82:83], v[82:83], v[82:83]
	v_pk_mul_f32 v[84:85], v[84:85], v[84:85]
	v_cvt_pk_bf16_f32 v164, v82, v83
	v_cvt_pk_bf16_f32 v165, v84, v85
	v_max_f32_e32 v78, 0, v54
	v_max_f32_e32 v79, 0, v55
	v_max_f32_e32 v80, 0, v56
	v_max_f32_e32 v81, 0, v57
	v_pk_mul_f32 v[78:79], v[78:79], v[78:79]
	v_pk_mul_f32 v[80:81], v[80:81], v[80:81]
	v_cvt_pk_bf16_f32 v166, v78, v79
	v_cvt_pk_bf16_f32 v167, v80, v81
	v_max_f32_e32 v82, 0, v50
	v_max_f32_e32 v83, 0, v51
	v_max_f32_e32 v84, 0, v52
	v_max_f32_e32 v85, 0, v53
	v_pk_mul_f32 v[82:83], v[82:83], v[82:83]
	v_pk_mul_f32 v[84:85], v[84:85], v[84:85]
	v_cvt_pk_bf16_f32 v168, v82, v83
	v_cvt_pk_bf16_f32 v169, v84, v85
	s_nop 1
	v_permlane16_swap_b32 v162, v164
	v_permlane16_swap_b32 v163, v165
	v_permlane16_swap_b32 v166, v168
	v_permlane16_swap_b32 v167, v169
	s_nop 1
	global_store_dwordx4 v[88:89], v[162:165], off sc1
	global_store_dwordx4 v[120:121], v[166:169], off sc1
	v_max_f32_e32 v78, 0, v46
	v_max_f32_e32 v79, 0, v47
	v_max_f32_e32 v80, 0, v48
	v_max_f32_e32 v81, 0, v49
	v_pk_mul_f32 v[78:79], v[78:79], v[78:79]
	v_pk_mul_f32 v[80:81], v[80:81], v[80:81]
	v_cvt_pk_bf16_f32 v170, v78, v79
	v_cvt_pk_bf16_f32 v171, v80, v81
	v_max_f32_e32 v82, 0, v42
	v_max_f32_e32 v83, 0, v43
	v_max_f32_e32 v84, 0, v44
	v_max_f32_e32 v85, 0, v45
	v_pk_mul_f32 v[82:83], v[82:83], v[82:83]
	v_pk_mul_f32 v[84:85], v[84:85], v[84:85]
	v_cvt_pk_bf16_f32 v172, v82, v83
	v_cvt_pk_bf16_f32 v173, v84, v85
	v_max_f32_e32 v78, 0, v38
	v_max_f32_e32 v79, 0, v39
	v_max_f32_e32 v80, 0, v40
	v_max_f32_e32 v81, 0, v41
	v_pk_mul_f32 v[78:79], v[78:79], v[78:79]
	v_pk_mul_f32 v[80:81], v[80:81], v[80:81]
	v_cvt_pk_bf16_f32 v174, v78, v79
	v_cvt_pk_bf16_f32 v175, v80, v81
	v_max_f32_e32 v82, 0, v34
	v_max_f32_e32 v83, 0, v35
	v_max_f32_e32 v84, 0, v36
	v_max_f32_e32 v85, 0, v37
	v_pk_mul_f32 v[82:83], v[82:83], v[82:83]
	v_pk_mul_f32 v[84:85], v[84:85], v[84:85]
	v_cvt_pk_bf16_f32 v176, v82, v83
	v_cvt_pk_bf16_f32 v177, v84, v85
	s_nop 1
	v_permlane16_swap_b32 v170, v172
	v_permlane16_swap_b32 v171, v173
	v_permlane16_swap_b32 v174, v176
	v_permlane16_swap_b32 v175, v177
	s_nop 1
	global_store_dwordx4 v[88:89], v[170:173], off offset:1024 sc1
	global_store_dwordx4 v[120:121], v[174:177], off offset:1024 sc1
	v_max_f32_e32 v78, 0, v30
	v_max_f32_e32 v79, 0, v31
	v_max_f32_e32 v80, 0, v32
	v_max_f32_e32 v81, 0, v33
	v_pk_mul_f32 v[78:79], v[78:79], v[78:79]
	v_pk_mul_f32 v[80:81], v[80:81], v[80:81]
	v_cvt_pk_bf16_f32 v162, v78, v79
	v_cvt_pk_bf16_f32 v163, v80, v81
	v_max_f32_e32 v82, 0, v18
	v_max_f32_e32 v83, 0, v19
	v_max_f32_e32 v84, 0, v20
	v_max_f32_e32 v85, 0, v21
	v_pk_mul_f32 v[82:83], v[82:83], v[82:83]
	v_pk_mul_f32 v[84:85], v[84:85], v[84:85]
	v_cvt_pk_bf16_f32 v164, v82, v83
	v_cvt_pk_bf16_f32 v165, v84, v85
	v_max_f32_e32 v78, 0, v12
	v_max_f32_e32 v79, 0, v13
	v_max_f32_e32 v80, 0, v14
	v_max_f32_e32 v81, 0, v15
	v_pk_mul_f32 v[78:79], v[78:79], v[78:79]
	v_pk_mul_f32 v[80:81], v[80:81], v[80:81]
	v_cvt_pk_bf16_f32 v166, v78, v79
	v_cvt_pk_bf16_f32 v167, v80, v81
	v_max_f32_e32 v82, 0, v4
	v_max_f32_e32 v83, 0, v5
	v_max_f32_e32 v84, 0, v6
	v_max_f32_e32 v85, 0, v7
	v_pk_mul_f32 v[82:83], v[82:83], v[82:83]
	v_pk_mul_f32 v[84:85], v[84:85], v[84:85]
	v_cvt_pk_bf16_f32 v168, v82, v83
	v_cvt_pk_bf16_f32 v169, v84, v85
	s_nop 1
	v_permlane16_swap_b32 v162, v164
	v_permlane16_swap_b32 v163, v165
	v_permlane16_swap_b32 v166, v168
	v_permlane16_swap_b32 v167, v169
	s_nop 1
	global_store_dwordx4 v[88:89], v[162:165], off offset:2048 sc1
	global_store_dwordx4 v[120:121], v[166:169], off offset:2048 sc1
	v_max_f32_e32 v78, 0, v0
	v_max_f32_e32 v79, 0, v1
	v_max_f32_e32 v80, 0, v2
	v_max_f32_e32 v81, 0, v3
	v_pk_mul_f32 v[78:79], v[78:79], v[78:79]
	v_pk_mul_f32 v[80:81], v[80:81], v[80:81]
	v_cvt_pk_bf16_f32 v170, v78, v79
	v_cvt_pk_bf16_f32 v171, v80, v81
	v_max_f32_e32 v82, 0, v26
	v_max_f32_e32 v83, 0, v27
	v_max_f32_e32 v84, 0, v28
	v_max_f32_e32 v85, 0, v29
	v_pk_mul_f32 v[82:83], v[82:83], v[82:83]
	v_pk_mul_f32 v[84:85], v[84:85], v[84:85]
	v_cvt_pk_bf16_f32 v172, v82, v83
	v_cvt_pk_bf16_f32 v173, v84, v85
	v_max_f32_e32 v78, 0, v22
	v_max_f32_e32 v79, 0, v23
	v_max_f32_e32 v80, 0, v24
	v_max_f32_e32 v81, 0, v25
	v_pk_mul_f32 v[78:79], v[78:79], v[78:79]
	v_pk_mul_f32 v[80:81], v[80:81], v[80:81]
	v_cvt_pk_bf16_f32 v174, v78, v79
	v_cvt_pk_bf16_f32 v175, v80, v81
	v_max_f32_e32 v82, 0, v8
	v_max_f32_e32 v83, 0, v9
	v_max_f32_e32 v84, 0, v10
	v_max_f32_e32 v85, 0, v11
	v_pk_mul_f32 v[82:83], v[82:83], v[82:83]
	v_pk_mul_f32 v[84:85], v[84:85], v[84:85]
	v_cvt_pk_bf16_f32 v176, v82, v83
	v_cvt_pk_bf16_f32 v177, v84, v85
	s_nop 1
	v_permlane16_swap_b32 v170, v172
	v_permlane16_swap_b32 v171, v173
	v_permlane16_swap_b32 v174, v176
	v_permlane16_swap_b32 v175, v177
	s_nop 1
	global_store_dwordx4 v[88:89], v[170:173], off offset:3072 sc1
	global_store_dwordx4 v[120:121], v[174:177], off offset:3072 sc1

.Lpfa_skip_m2:
	s_mov_b32 s99, 1
	v_or_b32_e32 v0, s43, v127
	v_and_b32_e32 v1, 64, v126
	v_add_u32_e32 v0, v0, v128
	v_lshlrev_b32_e32 v2, 2, v125
	v_or3_b32 v6, v2, v1, s34
	v_ashrrev_i32_e32 v1, 31, v0
	v_lshlrev_b64 v[2:3], 11, v[0:1]
	v_lshl_add_u64 v[2:3], s[6:7], 0, v[2:3]
	v_lshlrev_b32_e32 v6, 1, v6
	v_and_b32_e32 v9, 1, v125
	v_mul_u32_u24_e32 v9, 24, v9
	v_add_u32_e32 v6, v6, v9
	v_mov_b32_e32 v7, v17
	v_cvt_pk_bf16_f32 v160, v86, v87
	v_cvt_pk_bf16_f32 v161, v88, v89
	v_cvt_pk_bf16_f32 v162, v82, v83
	v_cvt_pk_bf16_f32 v163, v84, v85
	v_cvt_pk_bf16_f32 v164, v74, v75
	v_cvt_pk_bf16_f32 v165, v76, v77
	v_cvt_pk_bf16_f32 v166, v66, v67
	v_cvt_pk_bf16_f32 v167, v68, v69
	v_lshl_add_u64 v[2:3], v[2:3], 0, v[6:7]
	s_nop 1
	v_permlane16_swap_b32 v160, v162
	v_permlane16_swap_b32 v161, v163
	v_permlane16_swap_b32 v164, v166
	v_permlane16_swap_b32 v165, v167
	s_nop 1
	global_store_dwordx4 v[2:3], v[160:163], off sc1
	global_store_dwordx4 v[2:3], v[164:167], off offset:64 sc1
	v_cvt_pk_bf16_f32 v168, v54, v55
	v_cvt_pk_bf16_f32 v169, v56, v57
	v_cvt_pk_bf16_f32 v170, v46, v47
	v_cvt_pk_bf16_f32 v171, v48, v49
	v_cvt_pk_bf16_f32 v172, v38, v39
	v_cvt_pk_bf16_f32 v173, v40, v41
	v_cvt_pk_bf16_f32 v174, v34, v35
	v_cvt_pk_bf16_f32 v175, v36, v37
	v_or_b32_e32 v2, 16, v0
	v_ashrrev_i32_e32 v3, 31, v2
	v_lshlrev_b64 v[2:3], 11, v[2:3]
	v_lshl_add_u64 v[2:3], s[6:7], 0, v[2:3]
	v_lshl_add_u64 v[2:3], v[2:3], 0, v[6:7]
	s_nop 1
	v_permlane16_swap_b32 v168, v170
	v_permlane16_swap_b32 v169, v171
	v_permlane16_swap_b32 v172, v174
	v_permlane16_swap_b32 v173, v175
	s_nop 1
	global_store_dwordx4 v[2:3], v[168:171], off sc1
	global_store_dwordx4 v[2:3], v[172:175], off offset:64 sc1
	v_cvt_pk_bf16_f32 v160, v70, v71
	v_cvt_pk_bf16_f32 v161, v72, v73
	v_cvt_pk_bf16_f32 v162, v62, v63
	v_cvt_pk_bf16_f32 v163, v64, v65
	v_cvt_pk_bf16_f32 v164, v50, v51
	v_cvt_pk_bf16_f32 v165, v52, v53
	v_cvt_pk_bf16_f32 v166, v42, v43
	v_cvt_pk_bf16_f32 v167, v44, v45
	v_or_b32_e32 v2, 32, v0
	v_ashrrev_i32_e32 v3, 31, v2
	v_lshlrev_b64 v[2:3], 11, v[2:3]
	v_lshl_add_u64 v[2:3], s[6:7], 0, v[2:3]
	v_lshl_add_u64 v[2:3], v[2:3], 0, v[6:7]
	v_or_b32_e32 v0, 48, v0
	v_ashrrev_i32_e32 v1, 31, v0
	v_lshlrev_b64 v[0:1], 11, v[0:1]
	v_lshl_add_u64 v[0:1], s[6:7], 0, v[0:1]
	s_nop 1
	v_permlane16_swap_b32 v160, v162
	v_permlane16_swap_b32 v161, v163
	v_permlane16_swap_b32 v164, v166
	v_permlane16_swap_b32 v165, v167
	s_nop 1
	global_store_dwordx4 v[2:3], v[160:163], off sc1
	global_store_dwordx4 v[2:3], v[164:167], off offset:64 sc1
	v_cvt_pk_bf16_f32 v168, v26, v27
	v_cvt_pk_bf16_f32 v169, v28, v29
	v_cvt_pk_bf16_f32 v170, v30, v31
	v_cvt_pk_bf16_f32 v171, v32, v33
	v_cvt_pk_bf16_f32 v172, v78, v79
	v_cvt_pk_bf16_f32 v173, v80, v81
	v_cvt_pk_bf16_f32 v174, v58, v59
	v_cvt_pk_bf16_f32 v175, v60, v61
	v_lshl_add_u64 v[0:1], v[0:1], 0, v[6:7]
	s_nop 1
	v_permlane16_swap_b32 v168, v170
	v_permlane16_swap_b32 v169, v171
	v_permlane16_swap_b32 v172, v174
	v_permlane16_swap_b32 v173, v175
	s_nop 1
	global_store_dwordx4 v[0:1], v[168:171], off sc1
	global_store_dwordx4 v[0:1], v[172:175], off offset:64 sc1
